# attention unit epilogue: the 16 ds_bpermute row reductions (xor 1,2,4,8 within 16 lanes) replaced by DPP moves (quad_perm, row_half_mirror, row_mirror), bit-identical sums
# speedup vs baseline: 1.0072x; 1.0072x over previous
.LBB0_398:
	s_or_b64 exec, exec, s[4:5]
	s_waitcnt lgkmcnt(0)
	v_add_u32_e32 v0, s42, v222
	ds_read_b128 v[2:5], v0 offset:128
	ds_read_b128 v[6:9], v0 offset:160
	s_lshl_b32 s4, s68, 6
	s_and_b32 s4, s4, 0xffffe000
	s_add_i32 s64, s64, 1
	s_waitcnt lgkmcnt(1)
	v_rcp_f32_e32 v10, v2
	v_rcp_f32_e32 v11, v3
	v_rcp_f32_e32 v12, v4
	v_rcp_f32_e32 v13, v5
	s_waitcnt lgkmcnt(0)
	v_rcp_f32_e32 v14, v6
	ds_read_b128 v[2:5], v0 offset:192
	v_rcp_f32_e32 v15, v7
	v_rcp_f32_e32 v80, v8
	v_rcp_f32_e32 v81, v9
	ds_read_b128 v[6:9], v0 offset:224
	v_mul_f32_e32 v16, v16, v10
	s_waitcnt lgkmcnt(1)
	v_rcp_f32_e32 v0, v2
	v_rcp_f32_e32 v2, v3
	v_rcp_f32_e32 v3, v4
	v_rcp_f32_e32 v4, v5
	s_waitcnt lgkmcnt(0)
	v_rcp_f32_e32 v5, v6
	v_rcp_f32_e32 v6, v7
	v_rcp_f32_e32 v7, v8
	v_rcp_f32_e32 v8, v9
	v_lshl_add_u32 v9, s70, 13, v223
	v_cvt_pk_bf16_f32 v16, v16, s0
	s_waitcnt vmcnt(0) lgkmcnt(0)
	s_barrier
	ds_write_b16 v9, v16
	v_mul_f32_e32 v16, v32, v10
	v_cvt_pk_bf16_f32 v16, v16, s0
	ds_write_b16 v9, v16 offset:64
	v_mul_f32_e32 v16, v48, v10
	v_mul_f32_e32 v10, v64, v10
	v_cvt_pk_bf16_f32 v10, v10, s0
	ds_write_b16 v9, v10 offset:192
	v_mul_f32_e32 v10, v17, v11
	v_cvt_pk_bf16_f32 v10, v10, s0
	ds_write_b16 v9, v10 offset:256
	v_mul_f32_e32 v10, v33, v11
	v_cvt_pk_bf16_f32 v10, v10, s0
	ds_write_b16 v9, v10 offset:320
	v_mul_f32_e32 v10, v49, v11
	v_cvt_pk_bf16_f32 v10, v10, s0
	ds_write_b16 v9, v10 offset:384
	v_mul_f32_e32 v10, v65, v11
	v_cvt_pk_bf16_f32 v10, v10, s0
	ds_write_b16 v9, v10 offset:448
	v_mul_f32_e32 v10, v18, v12
	v_cvt_pk_bf16_f32 v10, v10, s0
	ds_write_b16 v9, v10 offset:512
	v_mul_f32_e32 v10, v34, v12
	v_cvt_pk_bf16_f32 v10, v10, s0
	ds_write_b16 v9, v10 offset:576
	v_mul_f32_e32 v10, v50, v12
	v_cvt_pk_bf16_f32 v10, v10, s0
	ds_write_b16 v9, v10 offset:640
	v_mul_f32_e32 v10, v66, v12
	v_cvt_pk_bf16_f32 v10, v10, s0
	ds_write_b16 v9, v10 offset:704
	v_mul_f32_e32 v10, v19, v13
	v_cvt_pk_bf16_f32 v10, v10, s0
	ds_write_b16 v9, v10 offset:768
	v_mul_f32_e32 v10, v35, v13
	v_cvt_pk_bf16_f32 v10, v10, s0
	ds_write_b16 v9, v10 offset:832
	v_mul_f32_e32 v10, v51, v13
	v_cvt_pk_bf16_f32 v10, v10, s0
	ds_write_b16 v9, v10 offset:896
	v_mul_f32_e32 v10, v67, v13
	v_cvt_pk_bf16_f32 v10, v10, s0
	ds_write_b16 v9, v10 offset:960
	v_mul_f32_e32 v10, v20, v14
	v_cvt_pk_bf16_f32 v10, v10, s0
	ds_write_b16 v9, v10 offset:2048
	v_mul_f32_e32 v10, v36, v14
	v_cvt_pk_bf16_f32 v10, v10, s0
	ds_write_b16 v9, v10 offset:2112
	v_mul_f32_e32 v10, v52, v14
	v_cvt_pk_bf16_f32 v10, v10, s0
	ds_write_b16 v9, v10 offset:2176
	v_mul_f32_e32 v10, v68, v14
	v_cvt_pk_bf16_f32 v10, v10, s0
	ds_write_b16 v9, v10 offset:2240
	v_mul_f32_e32 v10, v21, v15
	v_cvt_pk_bf16_f32 v10, v10, s0
	ds_write_b16 v9, v10 offset:2304
	v_mul_f32_e32 v10, v37, v15
	v_cvt_pk_bf16_f32 v10, v10, s0
	ds_write_b16 v9, v10 offset:2368
	v_mul_f32_e32 v10, v53, v15
	v_cvt_pk_bf16_f32 v10, v10, s0
	ds_write_b16 v9, v10 offset:2432
	v_mul_f32_e32 v10, v69, v15
	v_cvt_pk_bf16_f32 v10, v10, s0
	ds_write_b16 v9, v10 offset:2496
	v_mul_f32_e32 v10, v22, v80
	v_cvt_pk_bf16_f32 v10, v10, s0
	ds_write_b16 v9, v10 offset:2560
	v_mul_f32_e32 v10, v38, v80
	v_cvt_pk_bf16_f32 v10, v10, s0
	ds_write_b16 v9, v10 offset:2624
	v_mul_f32_e32 v10, v54, v80
	v_cvt_pk_bf16_f32 v10, v10, s0
	ds_write_b16 v9, v10 offset:2688
	v_mul_f32_e32 v10, v70, v80
	v_cvt_pk_bf16_f32 v10, v10, s0
	ds_write_b16 v9, v10 offset:2752
	v_mul_f32_e32 v10, v23, v81
	v_cvt_pk_bf16_f32 v10, v10, s0
	ds_write_b16 v9, v10 offset:2816
	v_mul_f32_e32 v10, v39, v81
	v_cvt_pk_bf16_f32 v10, v10, s0
	ds_write_b16 v9, v10 offset:2880
	v_mul_f32_e32 v10, v55, v81
	v_cvt_pk_bf16_f32 v10, v10, s0
	ds_write_b16 v9, v10 offset:2944
	v_mul_f32_e32 v10, v71, v81
	v_cvt_pk_bf16_f32 v10, v10, s0
	ds_write_b16 v9, v10 offset:3008
	v_mul_f32_e32 v10, v24, v0
	v_cvt_pk_bf16_f32 v10, v10, s0
	ds_write_b16 v9, v10 offset:4096
	v_mul_f32_e32 v10, v40, v0
	v_cvt_pk_bf16_f32 v10, v10, s0
	ds_write_b16 v9, v10 offset:4160
	v_mul_f32_e32 v10, v56, v0
	v_mul_f32_e32 v0, v72, v0
	v_cvt_pk_bf16_f32 v0, v0, s0
	ds_write_b16 v9, v0 offset:4288
	v_mul_f32_e32 v0, v25, v2
	v_cvt_pk_bf16_f32 v0, v0, s0
	ds_write_b16 v9, v0 offset:4352
	v_mul_f32_e32 v0, v41, v2
	v_cvt_pk_bf16_f32 v0, v0, s0
	ds_write_b16 v9, v0 offset:4416
	v_mul_f32_e32 v0, v57, v2
	v_cvt_pk_bf16_f32 v0, v0, s0
	ds_write_b16 v9, v0 offset:4480
	v_mul_f32_e32 v0, v73, v2
	v_cvt_pk_bf16_f32 v0, v0, s0
	ds_write_b16 v9, v0 offset:4544
	v_mul_f32_e32 v0, v26, v3
	v_cvt_pk_bf16_f32 v0, v0, s0
	ds_write_b16 v9, v0 offset:4608
	v_mul_f32_e32 v0, v42, v3
	v_cvt_pk_bf16_f32 v0, v0, s0
	ds_write_b16 v9, v0 offset:4672
	v_mul_f32_e32 v0, v58, v3
	v_cvt_pk_bf16_f32 v0, v0, s0
	ds_write_b16 v9, v0 offset:4736
	v_mul_f32_e32 v0, v74, v3
	v_cvt_pk_bf16_f32 v0, v0, s0
	ds_write_b16 v9, v0 offset:4800
	v_mul_f32_e32 v0, v27, v4
	v_cvt_pk_bf16_f32 v0, v0, s0
	ds_write_b16 v9, v0 offset:4864
	v_mul_f32_e32 v0, v43, v4
	v_cvt_pk_bf16_f32 v0, v0, s0
	ds_write_b16 v9, v0 offset:4928
	v_mul_f32_e32 v0, v59, v4
	v_cvt_pk_bf16_f32 v0, v0, s0
	ds_write_b16 v9, v0 offset:4992
	v_mul_f32_e32 v0, v75, v4
	v_cvt_pk_bf16_f32 v0, v0, s0
	ds_write_b16 v9, v0 offset:5056
	v_mul_f32_e32 v0, v28, v5
	v_cvt_pk_bf16_f32 v0, v0, s0
	ds_write_b16 v9, v0 offset:6144
	v_mul_f32_e32 v0, v44, v5
	v_cvt_pk_bf16_f32 v0, v0, s0
	ds_write_b16 v9, v0 offset:6208
	v_mul_f32_e32 v0, v60, v5
	v_cvt_pk_bf16_f32 v0, v0, s0
	ds_write_b16 v9, v0 offset:6272
	v_mul_f32_e32 v0, v76, v5
	v_cvt_pk_bf16_f32 v0, v0, s0
	ds_write_b16 v9, v0 offset:6336
	v_mul_f32_e32 v0, v29, v6
	v_cvt_pk_bf16_f32 v0, v0, s0
	ds_write_b16 v9, v0 offset:6400
	v_mul_f32_e32 v0, v45, v6
	v_cvt_pk_bf16_f32 v0, v0, s0
	ds_write_b16 v9, v0 offset:6464
	v_mul_f32_e32 v0, v61, v6
	v_cvt_pk_bf16_f32 v0, v0, s0
	ds_write_b16 v9, v0 offset:6528
	v_mul_f32_e32 v0, v77, v6
	v_cvt_pk_bf16_f32 v0, v0, s0
	ds_write_b16 v9, v0 offset:6592
	v_mul_f32_e32 v0, v30, v7
	v_cvt_pk_bf16_f32 v0, v0, s0
	ds_write_b16 v9, v0 offset:6656
	v_mul_f32_e32 v0, v46, v7
	v_cvt_pk_bf16_f32 v0, v0, s0
	ds_write_b16 v9, v0 offset:6720
	v_mul_f32_e32 v0, v62, v7
	v_cvt_pk_bf16_f32 v0, v0, s0
	ds_write_b16 v9, v0 offset:6784
	v_mul_f32_e32 v0, v78, v7
	v_cvt_pk_bf16_f32 v0, v0, s0
	ds_write_b16 v9, v0 offset:6848
	v_mul_f32_e32 v0, v31, v8
	v_cvt_pk_bf16_f32 v0, v0, s0
	ds_write_b16 v9, v0 offset:6912
	v_mul_f32_e32 v0, v47, v8
	v_cvt_pk_bf16_f32 v0, v0, s0
	ds_write_b16 v9, v0 offset:6976
	v_mul_f32_e32 v0, v63, v8
	v_cvt_pk_bf16_f32 v0, v0, s0
	ds_write_b16 v9, v0 offset:7040
	v_mul_f32_e32 v0, v79, v8
	v_cvt_pk_bf16_f32 v0, v0, s0
	ds_write_b16 v9, v0 offset:7104
	v_or_b32_e32 v0, s69, v217
	v_cvt_pk_bf16_f32 v16, v16, s0
	v_cvt_pk_bf16_f32 v10, v10, s0
	v_lshlrev_b32_e32 v2, 8, v0
	ds_write_b16 v9, v16 offset:128
	ds_write_b16 v9, v10 offset:4224
	v_add_u32_e32 v34, s4, v206
	v_and_b32_e32 v2, 0x1300, v2
	s_waitcnt lgkmcnt(0)
	s_barrier
	v_add_u32_e32 v6, v34, v2
	ds_read_b128 v[2:5], v6
	ds_read_b128 v[6:9], v6 offset:32768
	v_or_b32_e32 v20, 4, v0
	s_waitcnt lgkmcnt(1)
	v_lshlrev_b32_e32 v10, 16, v5
	v_and_b32_e32 v11, 0xffff0000, v5
	s_waitcnt lgkmcnt(0)
	v_lshlrev_b32_e32 v12, 16, v9
	v_and_b32_e32 v13, 0xffff0000, v9
	v_lshlrev_b32_e32 v14, 16, v4
	v_and_b32_e32 v15, 0xffff0000, v4
	v_lshlrev_b32_e32 v4, 16, v8
	v_and_b32_e32 v5, 0xffff0000, v8
	v_lshlrev_b32_e32 v8, 16, v3
	v_and_b32_e32 v9, 0xffff0000, v3
	v_lshlrev_b32_e32 v18, 16, v2
	v_and_b32_e32 v19, 0xffff0000, v2
	v_lshlrev_b32_e32 v2, 16, v6
	v_and_b32_e32 v3, 0xffff0000, v6
	v_lshlrev_b32_e32 v16, 16, v7
	v_and_b32_e32 v17, 0xffff0000, v7
	v_pk_fma_f32 v[18:19], v[186:187], v[2:3], v[18:19] neg_lo:[1,0,0] neg_hi:[1,0,0]
	v_pk_fma_f32 v[16:17], v[186:187], v[16:17], v[8:9] neg_lo:[1,0,0] neg_hi:[1,0,0]
	v_pk_mul_f32 v[2:3], v[18:19], v[18:19]
	v_pk_mul_f32 v[8:9], v[16:17], v[16:17]
	v_add_f32_e32 v2, v2, v3
	v_pk_fma_f32 v[14:15], v[186:187], v[4:5], v[14:15] neg_lo:[1,0,0] neg_hi:[1,0,0]
	v_add_f32_e32 v2, v8, v2
	v_pk_mul_f32 v[4:5], v[14:15], v[14:15]
	v_add_f32_e32 v2, v9, v2
	v_pk_fma_f32 v[12:13], v[186:187], v[12:13], v[10:11] neg_lo:[1,0,0] neg_hi:[1,0,0]
	v_add_f32_e32 v2, v4, v2
	v_pk_mul_f32 v[10:11], v[12:13], v[12:13]
	v_add_f32_e32 v2, v5, v2
	v_add_f32_e32 v2, v10, v2
	v_add_f32_e32 v2, v11, v2
	s_nop 1
	v_mov_b32_dpp v3, v2 quad_perm:[1,0,3,2] row_mask:0xf bank_mask:0xf
	s_waitcnt lgkmcnt(0)
	v_add_f32_e32 v2, v2, v3
	s_nop 1
	v_mov_b32_dpp v3, v2 quad_perm:[2,3,0,1] row_mask:0xf bank_mask:0xf
	s_waitcnt lgkmcnt(0)
	v_add_f32_e32 v2, v2, v3
	s_nop 1
	v_mov_b32_dpp v3, v2 row_half_mirror row_mask:0xf bank_mask:0xf
	s_waitcnt lgkmcnt(0)
	v_add_f32_e32 v2, v2, v3
	s_nop 1
	v_mov_b32_dpp v3, v2 row_mirror row_mask:0xf bank_mask:0xf
	s_waitcnt lgkmcnt(0)
	v_add_f32_e32 v2, v2, v3
	v_fmamk_f32 v2, v2, 0x3c000000, v207
	v_mul_f32_e32 v3, 0x4f800000, v2
	v_cmp_gt_f32_e32 vcc, s63, v2
	s_nop 1
	v_cndmask_b32_e32 v4, v2, v3, vcc
	v_sqrt_f32_e32 v5, v4
	v_lshl_add_u64 v[2:3], v[188:189], 0, s[38:39]
	v_add_u32_e32 v6, -1, v5
	v_fma_f32 v7, -v6, v5, v4
	v_cmp_ge_f32_e64 s[4:5], 0, v7
	v_add_u32_e32 v7, 1, v5
	s_nop 0
	v_cndmask_b32_e64 v6, v5, v6, s[4:5]
	v_fma_f32 v5, -v7, v5, v4
	v_cmp_lt_f32_e64 s[4:5], 0, v5
	s_nop 1
	v_cndmask_b32_e64 v5, v6, v7, s[4:5]
	v_mul_f32_e32 v6, 0x37800000, v5
	v_cndmask_b32_e32 v5, v5, v6, vcc
	v_cmp_class_f32_e32 vcc, v4, v224
	s_nop 1
	v_cndmask_b32_e32 v21, v5, v4, vcc
	v_lshlrev_b32_e32 v4, 8, v20
	v_and_b32_e32 v4, 0x1700, v4
	v_add_u32_e32 v8, v34, v4
	ds_read_b128 v[4:7], v8
	ds_read_b128 v[8:11], v8 offset:32768
	v_div_scale_f32 v32, s[4:5], v21, v21, 1.0
	v_rcp_f32_e32 v33, v32
	s_waitcnt lgkmcnt(1)
	v_lshlrev_b32_e32 v22, 16, v7
	v_and_b32_e32 v23, 0xffff0000, v7
	s_waitcnt lgkmcnt(0)
	v_lshlrev_b32_e32 v24, 16, v11
	v_and_b32_e32 v25, 0xffff0000, v11
	v_lshlrev_b32_e32 v26, 16, v6
	v_and_b32_e32 v27, 0xffff0000, v6
	v_lshlrev_b32_e32 v6, 16, v10
	v_and_b32_e32 v7, 0xffff0000, v10
	v_lshlrev_b32_e32 v10, 16, v5
	v_and_b32_e32 v11, 0xffff0000, v5
	v_lshlrev_b32_e32 v30, 16, v4
	v_and_b32_e32 v31, 0xffff0000, v4
	v_lshlrev_b32_e32 v4, 16, v8
	v_and_b32_e32 v5, 0xffff0000, v8
	v_lshlrev_b32_e32 v28, 16, v9
	v_and_b32_e32 v29, 0xffff0000, v9
	v_pk_fma_f32 v[30:31], v[186:187], v[4:5], v[30:31] neg_lo:[1,0,0] neg_hi:[1,0,0]
	v_pk_fma_f32 v[28:29], v[186:187], v[28:29], v[10:11] neg_lo:[1,0,0] neg_hi:[1,0,0]
	v_pk_mul_f32 v[4:5], v[30:31], v[30:31]
	v_pk_mul_f32 v[10:11], v[28:29], v[28:29]
	v_add_f32_e32 v4, v4, v5
	v_pk_fma_f32 v[26:27], v[186:187], v[6:7], v[26:27] neg_lo:[1,0,0] neg_hi:[1,0,0]
	v_add_f32_e32 v4, v10, v4
	v_pk_mul_f32 v[6:7], v[26:27], v[26:27]
	v_add_f32_e32 v4, v11, v4
	v_pk_fma_f32 v[22:23], v[186:187], v[24:25], v[22:23] neg_lo:[1,0,0] neg_hi:[1,0,0]
	v_add_f32_e32 v4, v6, v4
	v_pk_mul_f32 v[24:25], v[22:23], v[22:23]
	v_add_f32_e32 v4, v7, v4
	v_add_f32_e32 v4, v24, v4
	v_add_f32_e32 v4, v25, v4
	s_nop 1
	v_mov_b32_dpp v5, v4 quad_perm:[1,0,3,2] row_mask:0xf bank_mask:0xf
	v_fma_f32 v6, -v32, v33, 1.0
	v_fmac_f32_e32 v33, v6, v33
	v_div_scale_f32 v6, vcc, 1.0, v21, 1.0
	s_waitcnt lgkmcnt(0)
	v_add_f32_e32 v4, v4, v5
	s_nop 1
	v_mov_b32_dpp v5, v4 quad_perm:[2,3,0,1] row_mask:0xf bank_mask:0xf
	v_mul_f32_e32 v7, v6, v33
	v_fma_f32 v8, -v32, v7, v6
	v_fmac_f32_e32 v7, v8, v33
	v_fma_f32 v6, -v32, v7, v6
	s_waitcnt lgkmcnt(0)
	v_add_f32_e32 v9, v4, v5
	s_nop 1
	v_mov_b32_dpp v10, v9 row_half_mirror row_mask:0xf bank_mask:0xf
	v_div_fmas_f32 v4, v6, v33, v7
	v_div_fixup_f32 v8, v4, v21, 1.0
	v_pk_mul_f32 v[4:5], v[18:19], v[8:9] op_sel_hi:[1,0]
	s_waitcnt lgkmcnt(0)
	v_add_f32_e32 v9, v9, v10
	s_nop 1
	v_mov_b32_dpp v10, v9 row_mirror row_mask:0xf bank_mask:0xf
	v_pk_mul_f32 v[6:7], v[16:17], v[8:9] op_sel_hi:[1,0]
	v_cvt_pk_bf16_f32 v4, v4, v5
	v_cvt_pk_bf16_f32 v5, v6, v7
	v_pk_mul_f32 v[6:7], v[14:15], v[8:9] op_sel_hi:[1,0]
	s_nop 0
	v_cvt_pk_bf16_f32 v6, v6, v7
	s_waitcnt lgkmcnt(0)
	v_add_f32_e32 v7, v9, v10
	v_fmamk_f32 v7, v7, 0x3c000000, v207
	v_mul_f32_e32 v9, 0x4f800000, v7
	v_cmp_gt_f32_e32 vcc, s63, v7
	s_nop 1
	v_cndmask_b32_e32 v10, v7, v9, vcc
	v_sqrt_f32_e32 v11, v10
	v_pk_mul_f32 v[8:9], v[12:13], v[8:9] op_sel_hi:[1,0]
	v_add_u32_e32 v12, -1, v11
	v_fma_f32 v13, -v12, v11, v10
	v_cmp_ge_f32_e64 s[4:5], 0, v13
	v_add_u32_e32 v13, 1, v11
	v_cvt_pk_bf16_f32 v7, v8, v9
	v_cndmask_b32_e64 v12, v11, v12, s[4:5]
	v_fma_f32 v11, -v13, v11, v10
	v_cmp_lt_f32_e64 s[4:5], 0, v11
	v_lshl_add_u64 v[8:9], s[40:41], 0, v[0:1]
	v_lshlrev_b64 v[8:9], 12, v[8:9]
	v_cndmask_b32_e64 v11, v12, v13, s[4:5]
	v_mul_f32_e32 v12, 0x37800000, v11
	v_cndmask_b32_e32 v11, v11, v12, vcc
	v_cmp_class_f32_e32 vcc, v10, v224
	v_lshl_add_u64 v[8:9], v[2:3], 0, v[8:9]
	v_or_b32_e32 v12, 8, v0
	v_cndmask_b32_e32 v13, v11, v10, vcc
	v_div_scale_f32 v21, s[4:5], v13, v13, 1.0
	v_rcp_f32_e32 v35, v21
	global_store_dwordx4 v[8:9], v[4:7], off
	v_div_scale_f32 v36, vcc, 1.0, v13, 1.0
	s_nop 0
	v_lshlrev_b32_e32 v4, 8, v12
	v_and_b32_e32 v4, 0x1b00, v4
	v_fma_f32 v8, -v21, v35, 1.0
	v_add_u32_e32 v9, v34, v4
	ds_read_b128 v[4:7], v9
	v_fmac_f32_e32 v35, v8, v35
	ds_read_b128 v[8:11], v9 offset:32768
	v_or_b32_e32 v0, 12, v0
	s_waitcnt lgkmcnt(1)
	v_lshlrev_b32_e32 v14, 16, v7
	v_and_b32_e32 v15, 0xffff0000, v7
	s_waitcnt lgkmcnt(0)
	v_lshlrev_b32_e32 v16, 16, v11
	v_and_b32_e32 v17, 0xffff0000, v11
	v_lshlrev_b32_e32 v18, 16, v6
	v_and_b32_e32 v19, 0xffff0000, v6
	v_lshlrev_b32_e32 v6, 16, v10
	v_and_b32_e32 v7, 0xffff0000, v10
	v_lshlrev_b32_e32 v10, 16, v5
	v_and_b32_e32 v11, 0xffff0000, v5
	v_lshlrev_b32_e32 v32, 16, v4
	v_and_b32_e32 v33, 0xffff0000, v4
	v_lshlrev_b32_e32 v4, 16, v8
	v_and_b32_e32 v5, 0xffff0000, v8
	v_lshlrev_b32_e32 v24, 16, v9
	v_and_b32_e32 v25, 0xffff0000, v9
	v_pk_fma_f32 v[32:33], v[186:187], v[4:5], v[32:33] neg_lo:[1,0,0] neg_hi:[1,0,0]
	v_pk_fma_f32 v[24:25], v[186:187], v[24:25], v[10:11] neg_lo:[1,0,0] neg_hi:[1,0,0]
	v_pk_mul_f32 v[4:5], v[32:33], v[32:33]
	v_pk_mul_f32 v[10:11], v[24:25], v[24:25]
	v_add_f32_e32 v4, v4, v5
	v_pk_fma_f32 v[18:19], v[186:187], v[6:7], v[18:19] neg_lo:[1,0,0] neg_hi:[1,0,0]
	v_add_f32_e32 v4, v10, v4
	v_pk_mul_f32 v[6:7], v[18:19], v[18:19]
	v_add_f32_e32 v4, v11, v4
	v_pk_fma_f32 v[14:15], v[186:187], v[16:17], v[14:15] neg_lo:[1,0,0] neg_hi:[1,0,0]
	v_add_f32_e32 v4, v6, v4
	v_pk_mul_f32 v[16:17], v[14:15], v[14:15]
	v_add_f32_e32 v4, v7, v4
	v_add_f32_e32 v4, v16, v4
	v_add_f32_e32 v4, v17, v4
	s_nop 1
	v_mov_b32_dpp v5, v4 quad_perm:[1,0,3,2] row_mask:0xf bank_mask:0xf
	v_mul_f32_e32 v6, v36, v35
	v_fma_f32 v7, -v21, v6, v36
	v_fmac_f32_e32 v6, v7, v35
	v_fma_f32 v7, -v21, v6, v36
	s_waitcnt lgkmcnt(0)
	v_add_f32_e32 v9, v4, v5
	s_nop 1
	v_mov_b32_dpp v10, v9 quad_perm:[2,3,0,1] row_mask:0xf bank_mask:0xf
	v_div_fmas_f32 v4, v7, v35, v6
	v_div_fixup_f32 v8, v4, v13, 1.0
	v_pk_mul_f32 v[4:5], v[30:31], v[8:9] op_sel_hi:[1,0]
	v_mov_b32_e32 v21, v1
	s_waitcnt lgkmcnt(0)
	v_add_f32_e32 v9, v9, v10
	s_nop 1
	v_mov_b32_dpp v10, v9 row_half_mirror row_mask:0xf bank_mask:0xf
	v_pk_mul_f32 v[6:7], v[28:29], v[8:9] op_sel_hi:[1,0]
	v_cvt_pk_bf16_f32 v4, v4, v5
	v_cvt_pk_bf16_f32 v5, v6, v7
	v_pk_mul_f32 v[6:7], v[26:27], v[8:9] op_sel_hi:[1,0]
	s_waitcnt lgkmcnt(0)
	v_add_f32_e32 v10, v9, v10
	s_nop 1
	v_mov_b32_dpp v11, v10 row_mirror row_mask:0xf bank_mask:0xf
	v_pk_mul_f32 v[8:9], v[22:23], v[8:9] op_sel_hi:[1,0]
	v_cvt_pk_bf16_f32 v6, v6, v7
	v_cvt_pk_bf16_f32 v7, v8, v9
	s_waitcnt lgkmcnt(0)
	v_add_f32_e32 v8, v10, v11
	v_fmamk_f32 v8, v8, 0x3c000000, v207
	v_mul_f32_e32 v9, 0x4f800000, v8
	v_cmp_gt_f32_e32 vcc, s63, v8
	s_nop 1
	v_cndmask_b32_e32 v10, v8, v9, vcc
	v_sqrt_f32_e32 v11, v10
	v_lshl_add_u64 v[8:9], s[40:41], 0, v[20:21]
	v_lshlrev_b64 v[8:9], 12, v[8:9]
	v_lshl_add_u64 v[16:17], v[2:3], 0, v[8:9]
	v_add_u32_e32 v8, -1, v11
	v_fma_f32 v9, -v8, v11, v10
	v_cmp_ge_f32_e64 s[4:5], 0, v9
	v_add_u32_e32 v9, 1, v11
	global_store_dwordx4 v[16:17], v[4:7], off
	v_cndmask_b32_e64 v8, v11, v8, s[4:5]
	v_fma_f32 v11, -v9, v11, v10
	v_cmp_lt_f32_e64 s[4:5], 0, v11
	s_nop 1
	v_cndmask_b32_e64 v8, v8, v9, s[4:5]
	v_mul_f32_e32 v9, 0x37800000, v8
	v_cndmask_b32_e32 v8, v8, v9, vcc
	v_cmp_class_f32_e32 vcc, v10, v224
	s_nop 1
	v_cndmask_b32_e32 v13, v8, v10, vcc
	v_lshlrev_b32_e32 v8, 8, v0
	v_and_b32_e32 v8, 0x1f00, v8
	v_div_scale_f32 v30, s[4:5], v13, v13, 1.0
	v_add_u32_e32 v20, v34, v8
	v_rcp_f32_e32 v31, v30
	ds_read_b128 v[8:11], v20
	ds_read_b128 v[4:7], v20 offset:32768
	v_fma_f32 v16, -v30, v31, 1.0
	v_fmac_f32_e32 v31, v16, v31
	s_waitcnt lgkmcnt(1)
	v_lshlrev_b32_e32 v16, 16, v11
	v_and_b32_e32 v17, 0xffff0000, v11
	v_lshlrev_b32_e32 v22, 16, v10
	v_and_b32_e32 v23, 0xffff0000, v10
	s_waitcnt lgkmcnt(0)
	v_lshlrev_b32_e32 v10, 16, v6
	v_and_b32_e32 v11, 0xffff0000, v6
	v_pk_fma_f32 v[10:11], v[186:187], v[10:11], v[22:23] neg_lo:[1,0,0] neg_hi:[1,0,0]
	v_lshlrev_b32_e32 v22, 16, v9
	v_and_b32_e32 v23, 0xffff0000, v9
	v_lshlrev_b32_e32 v28, 16, v8
	v_and_b32_e32 v29, 0xffff0000, v8
	v_lshlrev_b32_e32 v8, 16, v4
	v_and_b32_e32 v9, 0xffff0000, v4
	v_lshlrev_b32_e32 v26, 16, v5
	v_and_b32_e32 v27, 0xffff0000, v5
	v_pk_fma_f32 v[8:9], v[186:187], v[8:9], v[28:29] neg_lo:[1,0,0] neg_hi:[1,0,0]
	v_pk_fma_f32 v[22:23], v[186:187], v[26:27], v[22:23] neg_lo:[1,0,0] neg_hi:[1,0,0]
	v_pk_mul_f32 v[4:5], v[8:9], v[8:9]
	v_pk_mul_f32 v[26:27], v[22:23], v[22:23]
	v_add_f32_e32 v4, v4, v5
	v_add_f32_e32 v4, v26, v4
	v_lshlrev_b32_e32 v20, 16, v7
	v_and_b32_e32 v21, 0xffff0000, v7
	v_pk_mul_f32 v[6:7], v[10:11], v[10:11]
	v_add_f32_e32 v4, v27, v4
	v_pk_fma_f32 v[16:17], v[186:187], v[20:21], v[16:17] neg_lo:[1,0,0] neg_hi:[1,0,0]
	v_add_f32_e32 v4, v6, v4
	v_pk_mul_f32 v[20:21], v[16:17], v[16:17]
	v_add_f32_e32 v4, v7, v4
	v_add_f32_e32 v4, v20, v4
	v_add_f32_e32 v4, v21, v4
	s_nop 1
	v_mov_b32_dpp v5, v4 quad_perm:[1,0,3,2] row_mask:0xf bank_mask:0xf
	v_div_scale_f32 v6, vcc, 1.0, v13, 1.0
	v_mul_f32_e32 v7, v6, v31
	v_fma_f32 v20, -v30, v7, v6
	s_waitcnt lgkmcnt(0)
	v_add_f32_e32 v4, v4, v5
	s_nop 1
	v_mov_b32_dpp v5, v4 quad_perm:[2,3,0,1] row_mask:0xf bank_mask:0xf
	v_fmac_f32_e32 v7, v20, v31
	v_fma_f32 v6, -v30, v7, v6
	v_div_fmas_f32 v6, v6, v31, v7
	v_div_fixup_f32 v20, v6, v13, 1.0
	s_waitcnt lgkmcnt(0)
	v_add_f32_e32 v21, v4, v5
	s_nop 1
	v_mov_b32_dpp v26, v21 row_half_mirror row_mask:0xf bank_mask:0xf
	v_pk_mul_f32 v[4:5], v[32:33], v[20:21] op_sel_hi:[1,0]
	v_pk_mul_f32 v[6:7], v[24:25], v[20:21] op_sel_hi:[1,0]
	v_cvt_pk_bf16_f32 v4, v4, v5
	v_cvt_pk_bf16_f32 v5, v6, v7
	s_waitcnt lgkmcnt(0)
	v_add_f32_e32 v13, v21, v26
	s_nop 1
	v_mov_b32_dpp v21, v13 row_mirror row_mask:0xf bank_mask:0xf
	s_waitcnt lgkmcnt(0)
	v_pk_mul_f32 v[6:7], v[18:19], v[20:21] op_sel_hi:[1,0]
	s_nop 0
	v_cvt_pk_bf16_f32 v6, v6, v7
	v_add_f32_e32 v7, v13, v21
	v_fmamk_f32 v7, v7, 0x3c000000, v207
	v_mul_f32_e32 v13, 0x4f800000, v7
	v_cmp_gt_f32_e32 vcc, s63, v7
	v_pk_mul_f32 v[14:15], v[14:15], v[20:21] op_sel_hi:[1,0]
	s_nop 0
	v_cndmask_b32_e32 v18, v7, v13, vcc
	v_sqrt_f32_e32 v19, v18
	v_cvt_pk_bf16_f32 v7, v14, v15
	v_mov_b32_e32 v13, v1
	v_lshl_add_u64 v[12:13], s[40:41], 0, v[12:13]
	v_add_u32_e32 v14, -1, v19
	v_fma_f32 v15, -v14, v19, v18
	v_cmp_ge_f32_e64 s[4:5], 0, v15
	v_add_u32_e32 v15, 1, v19
	v_lshlrev_b64 v[12:13], 12, v[12:13]
	v_cndmask_b32_e64 v14, v19, v14, s[4:5]
	v_fma_f32 v19, -v15, v19, v18
	v_cmp_lt_f32_e64 s[4:5], 0, v19
	v_lshl_add_u64 v[12:13], v[2:3], 0, v[12:13]
	global_store_dwordx4 v[12:13], v[4:7], off
	v_cndmask_b32_e64 v14, v14, v15, s[4:5]
	v_mul_f32_e32 v15, 0x37800000, v14
	v_cndmask_b32_e32 v14, v14, v15, vcc
	v_cmp_class_f32_e32 vcc, v18, v224
	s_nop 1
	v_cndmask_b32_e32 v14, v14, v18, vcc
	v_div_scale_f32 v15, s[4:5], v14, v14, 1.0
	v_rcp_f32_e32 v18, v15
	s_mov_b64 s[4:5], 0
	v_fma_f32 v4, -v15, v18, 1.0
	v_fmac_f32_e32 v18, v4, v18
	v_div_scale_f32 v4, vcc, 1.0, v14, 1.0
	v_mul_f32_e32 v5, v4, v18
	v_fma_f32 v6, -v15, v5, v4
	v_fmac_f32_e32 v5, v6, v18
	v_fma_f32 v4, -v15, v5, v4
	v_div_fmas_f32 v4, v4, v18, v5
	v_div_fixup_f32 v12, v4, v14, 1.0
	v_pk_mul_f32 v[4:5], v[8:9], v[12:13] op_sel_hi:[1,0]
	v_pk_mul_f32 v[6:7], v[22:23], v[12:13] op_sel_hi:[1,0]
	v_cvt_pk_bf16_f32 v4, v4, v5
	v_cvt_pk_bf16_f32 v5, v6, v7
	v_pk_mul_f32 v[6:7], v[10:11], v[12:13] op_sel_hi:[1,0]
	v_pk_mul_f32 v[8:9], v[16:17], v[12:13] op_sel_hi:[1,0]
	v_cvt_pk_bf16_f32 v6, v6, v7
	v_cvt_pk_bf16_f32 v7, v8, v9
	v_lshl_add_u64 v[8:9], s[40:41], 0, v[0:1]
	v_lshlrev_b64 v[8:9], 12, v[8:9]
	v_lshl_add_u64 v[2:3], v[2:3], 0, v[8:9]
	global_store_dwordx4 v[2:3], v[4:7], off
	s_waitcnt lgkmcnt(0)
	s_barrier
